# norm2 phase preamble de-serialised: all 12 gain/scale/shift loads issued together with counted waits (on top of nt stores + static prio)
# baseline (speedup 1.0000x reference)
.LBB0_1205:
	v_lshrrev_b32_e32 v0, 8, v80
	v_mul_hi_i32_i24_e32 v5, 0x1800, v0
	v_mul_i32_i24_e32 v4, 0x1800, v0
	v_lshlrev_b64 v[8:9], 2, v[4:5]
	v_lshl_add_u64 v[16:17], v[84:85], 0, v[8:9]
	v_lshl_add_u64 v[20:21], v[86:87], 0, v[8:9]
	global_load_dwordx4 v[40:43], v[16:17], off
	global_load_dwordx4 v[24:27], v[82:83], off
	global_load_dwordx4 v[44:47], v[16:17], off offset:1024
	global_load_dwordx4 v[28:31], v[82:83], off offset:1024
	global_load_dwordx4 v[48:51], v[16:17], off offset:2048
	global_load_dwordx4 v[32:35], v[82:83], off offset:2048
	global_load_dwordx4 v[52:55], v[16:17], off offset:3072
	global_load_dwordx4 v[36:39], v[82:83], off offset:3072
	global_load_dwordx4 v[0:3], v[20:21], off
	global_load_dwordx4 v[4:7], v[20:21], off offset:1024
	global_load_dwordx4 v[8:11], v[20:21], off offset:2048
	global_load_dwordx4 v[12:15], v[20:21], off offset:3072
	s_mov_b32 s0, -4
	v_mov_b64_e32 v[108:109], v[90:91]
	v_mov_b64_e32 v[110:111], v[88:89]
	s_waitcnt vmcnt(10)
	v_pk_add_f32 v[42:43], v[42:43], 1.0 op_sel_hi:[1,0]
	v_pk_add_f32 v[40:41], v[40:41], 1.0 op_sel_hi:[1,0]
	v_pk_mul_f32 v[92:93], v[26:27], v[42:43]
	v_pk_mul_f32 v[94:95], v[24:25], v[40:41]
	s_waitcnt vmcnt(8)
	v_pk_add_f32 v[46:47], v[46:47], 1.0 op_sel_hi:[1,0]
	v_pk_add_f32 v[44:45], v[44:45], 1.0 op_sel_hi:[1,0]
	v_pk_mul_f32 v[96:97], v[30:31], v[46:47]
	v_pk_mul_f32 v[98:99], v[28:29], v[44:45]
	s_waitcnt vmcnt(6)
	v_pk_add_f32 v[50:51], v[50:51], 1.0 op_sel_hi:[1,0]
	v_pk_add_f32 v[48:49], v[48:49], 1.0 op_sel_hi:[1,0]
	v_pk_mul_f32 v[100:101], v[34:35], v[50:51]
	v_pk_mul_f32 v[102:103], v[32:33], v[48:49]
	s_waitcnt vmcnt(4)
	v_pk_add_f32 v[54:55], v[54:55], 1.0 op_sel_hi:[1,0]
	v_pk_add_f32 v[52:53], v[52:53], 1.0 op_sel_hi:[1,0]
	v_pk_mul_f32 v[104:105], v[38:39], v[54:55]
	v_pk_mul_f32 v[106:107], v[36:37], v[52:53]
